# lead-half alignment barrier moved after the first SwiGLU epilogue block so it overlaps the trailing half's last MFMA block (on v19)
# baseline (speedup 1.0000x reference)
; #define PG8_STAGE(bufoff, gbase, voff) do { _Pragma("unroll") for (int _i = 0; _i < 2; ++_i) \
;         __builtin_amdgcn_global_load_lds((const unsigned*)((const char*)(gbase) + (voff)[_i]), (PG8_LAS unsigned*)(lds + (bufoff) + ldsw + _i * 8192), 16, 0, 0); } while (0)
; #define PG8_LDA(dst, b, h) do { _Pragma("unroll") for (int m = 0; m < 4; ++m) _Pragma("unroll") for (int k = 0; k < 2; ++k) dst[m][k] = *(const PG8_LAS bf16x8*)(lds + PG8_SA(b, h) + aoff + m * 2048 + k * 1024); } while (0)
; #define PG8_LDB(dst, b, h) do { _Pragma("unroll") for (int n = 0; n < 2; ++n) _Pragma("unroll") for (int k = 0; k < 2; ++k) dst[n][k] = *(const PG8_LAS bf16x8*)(lds + PG8_SB(b, h) + boff + n * 2048 + k * 1024); } while (0)
; #define PG8_MMA(ai, bj, At, Bt) do { __builtin_amdgcn_s_setprio(1); _Pragma("unroll") for (int m = 0; m < 4; ++m) _Pragma("unroll") for (int n = 0; n < 2; ++n) _Pragma("unroll") for (int k = 0; k < 2; ++k) \
;         acc[ai][bj][m][n] = __builtin_amdgcn_mfma_f32_16x16x32_bf16(Bt[n][k], At[m][k], acc[ai][bj][m][n], 0, 0, 0); __builtin_amdgcn_s_setprio(0); } while (0)
; #define PG8_WAIT_V(n) asm volatile("s_waitcnt vmcnt(" #n ")" ::: "memory")
; #define PG8_WAIT_L(n) asm volatile("s_waitcnt lgkmcnt(" #n ")" ::: "memory")
; #define PG8_BAR __builtin_amdgcn_s_barrier()
; #define PG8_SCHED __builtin_amdgcn_sched_barrier(0)
; template <class Epi, class Sched, bool ALIGN_EPI = false, bool SP2 = false>
; __device__ __forceinline__ void gemm_phase(PG8_LAS unsigned char* lds, const Gemm g, const Sched& S, const Epi& E) {
;     ...
;             PG8_LDB(B0, 0, 0); PG8_LDB(B1, 0, 1); PG8_SCHED; PG8_LDA(At, 0, 0); PG8_STAGE(PG8_SA(1, 1), a1 + hstep, voffA);
;             PG8_WAIT_V(8); PG8_WAIT_L(0); PG8_BAR; PG8_MMA(0, 0, At, B0); PG8_MMA(0, 1, At, B1); PG8_BAR; PG8_SCHED;
;             PG8_LDA(At, 0, 1); PG8_STAGE(PG8_SB(0, 0), b2, voffB); PG8_STAGE(PG8_SB(0, 1), b2 + hstep, voffB); PG8_STAGE(PG8_SA(0, 0), a2, voffA);
;             PG8_WAIT_V(8); PG8_WAIT_L(0); PG8_BAR; PG8_MMA(1, 0, At, B0); PG8_MMA(1, 1, At, B1); PG8_BAR; PG8_SCHED;
.LBB0_121:
	s_add_u32 s22, s20, 0xfffc0080
	s_addc_u32 s23, s21, -1
	s_add_i32 s90, 0, 0x10000
	s_cmp_eq_u32 s64, 12
	s_cselect_b32 s25, s13, s23
	s_cselect_b32 s24, s52, s22
	v_add_u32_e32 v158, s90, v160
	s_cselect_b32 s23, s15, s63
	s_cselect_b32 s22, s53, s62
	s_add_u32 s98, s22, s46
	s_addc_u32 s99, s23, s47
	s_add_u32 s100, s24, s46
	s_addc_u32 s101, s25, s47
	s_add_i32 s81, 0, 0x14000
	ds_read_b128 v[164:167], v158
	ds_read_b128 v[168:171], v158 offset:1024
	ds_read_b128 v[172:175], v158 offset:2048
	ds_read_b128 v[176:179], v158 offset:3072
	v_add_u32_e32 v158, s81, v160
	ds_read_b128 v[180:183], v158
	ds_read_b128 v[184:187], v158 offset:1024
	ds_read_b128 v[188:191], v158 offset:2048
	ds_read_b128 v[192:195], v158 offset:3072
	s_add_i32 m0, s35, 0xc000
	ds_read_b128 v[196:199], v163
	ds_read_b128 v[200:203], v163 offset:1024
	ds_read_b128 v[216:219], v163 offset:2048
	ds_read_b128 v[220:223], v163 offset:3072
	ds_read_b128 v[224:227], v163 offset:4096
	ds_read_b128 v[228:231], v163 offset:5120
	ds_read_b128 v[232:235], v163 offset:6144
	ds_read_b128 v[236:239], v163 offset:7168
	global_load_lds_dwordx4 v154, s[20:21]
	s_add_i32 m0, s35, 0xe000
	s_nop 0
	global_load_lds_dwordx4 v156, s[20:21]
	s_waitcnt vmcnt(8) lgkmcnt(0)
	s_barrier
	s_setprio 1
	v_mfma_f32_16x16x32_bf16 v[142:145], v[164:167], v[196:199], v[142:145]
	v_mfma_f32_16x16x32_bf16 v[138:141], v[172:175], v[196:199], v[138:141]
	v_mfma_f32_16x16x32_bf16 v[126:129], v[164:167], v[216:219], v[126:129]
	v_mfma_f32_16x16x32_bf16 v[122:125], v[172:175], v[216:219], v[122:125]
	v_mfma_f32_16x16x32_bf16 v[110:113], v[164:167], v[224:227], v[110:113]
	v_mfma_f32_16x16x32_bf16 v[106:109], v[172:175], v[224:227], v[106:109]
	v_mfma_f32_16x16x32_bf16 v[94:97], v[164:167], v[232:235], v[94:97]
	v_mfma_f32_16x16x32_bf16 v[90:93], v[172:175], v[232:235], v[90:93]
	v_mfma_f32_16x16x32_bf16 v[142:145], v[168:171], v[200:203], v[142:145]
	v_mfma_f32_16x16x32_bf16 v[138:141], v[176:179], v[200:203], v[138:141]
	v_mfma_f32_16x16x32_bf16 v[126:129], v[168:171], v[220:223], v[126:129]
	v_mfma_f32_16x16x32_bf16 v[122:125], v[176:179], v[220:223], v[122:125]
	v_mfma_f32_16x16x32_bf16 v[110:113], v[168:171], v[228:231], v[110:113]
	v_mfma_f32_16x16x32_bf16 v[106:109], v[176:179], v[228:231], v[106:109]
	v_mfma_f32_16x16x32_bf16 v[94:97], v[168:171], v[236:239], v[94:97]
	v_mfma_f32_16x16x32_bf16 v[90:93], v[176:179], v[236:239], v[90:93]
	v_mfma_f32_16x16x32_bf16 v[134:137], v[180:183], v[196:199], v[134:137]
	v_mfma_f32_16x16x32_bf16 v[130:133], v[188:191], v[196:199], v[130:133]
	v_mfma_f32_16x16x32_bf16 v[118:121], v[180:183], v[216:219], v[118:121]
	v_mfma_f32_16x16x32_bf16 v[114:117], v[188:191], v[216:219], v[114:117]
	v_mfma_f32_16x16x32_bf16 v[102:105], v[180:183], v[224:227], v[102:105]
	v_mfma_f32_16x16x32_bf16 v[98:101], v[188:191], v[224:227], v[98:101]
	v_mfma_f32_16x16x32_bf16 v[86:89], v[180:183], v[232:235], v[86:89]
	v_mfma_f32_16x16x32_bf16 v[82:85], v[188:191], v[232:235], v[82:85]
	v_mfma_f32_16x16x32_bf16 v[134:137], v[184:187], v[200:203], v[134:137]
	v_mfma_f32_16x16x32_bf16 v[130:133], v[192:195], v[200:203], v[130:133]
	v_mfma_f32_16x16x32_bf16 v[118:121], v[184:187], v[220:223], v[118:121]
	v_mfma_f32_16x16x32_bf16 v[114:117], v[192:195], v[220:223], v[114:117]
	v_mfma_f32_16x16x32_bf16 v[102:105], v[184:187], v[228:231], v[102:105]
	v_mfma_f32_16x16x32_bf16 v[98:101], v[192:195], v[228:231], v[98:101]
	v_mfma_f32_16x16x32_bf16 v[86:89], v[184:187], v[236:239], v[86:89]
	v_mfma_f32_16x16x32_bf16 v[82:85], v[192:195], v[236:239], v[82:85]
	s_setprio 0
	s_barrier
	s_add_i32 s65, s90, s34
	s_mov_b32 m0, s65
	ds_read_b128 v[196:199], v163 offset:16384
	ds_read_b128 v[200:203], v163 offset:17408
	ds_read_b128 v[216:219], v163 offset:18432
	ds_read_b128 v[220:223], v163 offset:19456
	ds_read_b128 v[224:227], v163 offset:20480
	ds_read_b128 v[228:231], v163 offset:21504
	ds_read_b128 v[232:235], v163 offset:22528
	ds_read_b128 v[236:239], v163 offset:23552
	global_load_lds_dwordx4 v148, s[22:23]
	s_add_i32 m0, s65, 0x2000
	s_add_u32 s66, s22, 0x40000
	s_addc_u32 s67, s23, 0
	s_add_i32 s65, s81, s34
	global_load_lds_dwordx4 v152, s[22:23]
	s_mov_b32 m0, s65
	s_nop 0
	global_load_lds_dwordx4 v148, s[66:67]
	s_add_i32 m0, s65, 0x2000
	s_nop 0
	global_load_lds_dwordx4 v152, s[66:67]
	s_mov_b32 m0, s35
	s_nop 0
	global_load_lds_dwordx4 v146, s[24:25]
	s_mov_b32 m0, s36
	s_nop 0
	global_load_lds_dwordx4 v150, s[24:25]
	s_waitcnt vmcnt(8) lgkmcnt(0)
	s_barrier
	s_setprio 1
	v_mfma_f32_16x16x32_bf16 v[78:81], v[164:167], v[196:199], v[78:81]
	v_mfma_f32_16x16x32_bf16 v[74:77], v[172:175], v[196:199], v[74:77]
	v_mfma_f32_16x16x32_bf16 v[62:65], v[164:167], v[216:219], v[62:65]
	v_mfma_f32_16x16x32_bf16 v[58:61], v[172:175], v[216:219], v[58:61]
	v_mfma_f32_16x16x32_bf16 v[46:49], v[164:167], v[224:227], v[46:49]
	v_mfma_f32_16x16x32_bf16 v[42:45], v[172:175], v[224:227], v[42:45]
	v_mfma_f32_16x16x32_bf16 v[30:33], v[164:167], v[232:235], v[30:33]
	v_mfma_f32_16x16x32_bf16 v[26:29], v[172:175], v[232:235], v[26:29]
	v_mfma_f32_16x16x32_bf16 v[78:81], v[168:171], v[200:203], v[78:81]
	v_mfma_f32_16x16x32_bf16 v[74:77], v[176:179], v[200:203], v[74:77]
	v_mfma_f32_16x16x32_bf16 v[62:65], v[168:171], v[220:223], v[62:65]
	v_mfma_f32_16x16x32_bf16 v[58:61], v[176:179], v[220:223], v[58:61]
	v_mfma_f32_16x16x32_bf16 v[46:49], v[168:171], v[228:231], v[46:49]
	v_mfma_f32_16x16x32_bf16 v[42:45], v[176:179], v[228:231], v[42:45]
	v_mfma_f32_16x16x32_bf16 v[30:33], v[168:171], v[236:239], v[30:33]
	v_mfma_f32_16x16x32_bf16 v[26:29], v[176:179], v[236:239], v[26:29]
	v_mfma_f32_16x16x32_bf16 v[70:73], v[180:183], v[196:199], v[70:73]
	v_mfma_f32_16x16x32_bf16 v[66:69], v[188:191], v[196:199], v[66:69]
	v_mfma_f32_16x16x32_bf16 v[54:57], v[180:183], v[216:219], v[54:57]
	v_mfma_f32_16x16x32_bf16 v[50:53], v[188:191], v[216:219], v[50:53]
	v_mfma_f32_16x16x32_bf16 v[38:41], v[180:183], v[224:227], v[38:41]
	v_mfma_f32_16x16x32_bf16 v[34:37], v[188:191], v[224:227], v[34:37]
	v_mfma_f32_16x16x32_bf16 v[22:25], v[180:183], v[232:235], v[22:25]
	v_mfma_f32_16x16x32_bf16 v[18:21], v[188:191], v[232:235], v[18:21]
	v_mfma_f32_16x16x32_bf16 v[70:73], v[184:187], v[200:203], v[70:73]
	v_mfma_f32_16x16x32_bf16 v[66:69], v[192:195], v[200:203], v[66:69]
	v_mfma_f32_16x16x32_bf16 v[54:57], v[184:187], v[220:223], v[54:57]
	v_mfma_f32_16x16x32_bf16 v[50:53], v[192:195], v[220:223], v[50:53]
	v_mfma_f32_16x16x32_bf16 v[38:41], v[184:187], v[228:231], v[38:41]
	v_mfma_f32_16x16x32_bf16 v[34:37], v[192:195], v[228:231], v[34:37]
	v_mfma_f32_16x16x32_bf16 v[22:25], v[184:187], v[236:239], v[22:25]
	v_mfma_f32_16x16x32_bf16 v[18:21], v[192:195], v[236:239], v[18:21]
	s_setprio 0
	s_barrier
; #define PG8_STAGE(bufoff, gbase, voff) do { _Pragma("unroll") for (int _i = 0; _i < 2; ++_i) \
;         __builtin_amdgcn_global_load_lds((const unsigned*)((const char*)(gbase) + (voff)[_i]), (PG8_LAS unsigned*)(lds + (bufoff) + ldsw + _i * 8192), 16, 0, 0); } while (0)
; #define PG8_LDA(dst, b, h) do { _Pragma("unroll") for (int m = 0; m < 4; ++m) _Pragma("unroll") for (int k = 0; k < 2; ++k) dst[m][k] = *(const PG8_LAS bf16x8*)(lds + PG8_SA(b, h) + aoff + m * 2048 + k * 1024); } while (0)
; #define PG8_LDB(dst, b, h) do { _Pragma("unroll") for (int n = 0; n < 2; ++n) _Pragma("unroll") for (int k = 0; k < 2; ++k) dst[n][k] = *(const PG8_LAS bf16x8*)(lds + PG8_SB(b, h) + boff + n * 2048 + k * 1024); } while (0)
; #define PG8_MMA(ai, bj, At, Bt) do { __builtin_amdgcn_s_setprio(1); _Pragma("unroll") for (int m = 0; m < 4; ++m) _Pragma("unroll") for (int n = 0; n < 2; ++n) _Pragma("unroll") for (int k = 0; k < 2; ++k) \
;         acc[ai][bj][m][n] = __builtin_amdgcn_mfma_f32_16x16x32_bf16(Bt[n][k], At[m][k], acc[ai][bj][m][n], 0, 0, 0); __builtin_amdgcn_s_setprio(0); } while (0)
; #define PG8_WAIT_V(n) asm volatile("s_waitcnt vmcnt(" #n ")" ::: "memory")
; #define PG8_WAIT_L(n) asm volatile("s_waitcnt lgkmcnt(" #n ")" ::: "memory")
; #define PG8_BAR __builtin_amdgcn_s_barrier()
; #define PG8_SCHED __builtin_amdgcn_sched_barrier(0)
; template <class Epi, class Sched, bool ALIGN_EPI = false, bool SP2 = false>
; __device__ __forceinline__ void gemm_phase(PG8_LAS unsigned char* lds, const Gemm g, const Sched& S, const Epi& E) {
;     ...
;             PG8_LDB(B0, 1, 0); PG8_LDB(B1, 1, 1); PG8_SCHED; PG8_LDA(At, 1, 0); PG8_STAGE(PG8_SA(0, 1), a2 + hstep, voffA);
;             PG8_WAIT_V(8); PG8_WAIT_L(0); PG8_BAR; PG8_MMA(0, 0, At, B0); PG8_MMA(0, 1, At, B1); PG8_BAR; PG8_SCHED;
;             PG8_LDA(At, 1, 1); PG8_STAGE(PG8_SB(1, 0), b3, voffB); PG8_STAGE(PG8_SB(1, 1), b3 + hstep, voffB); PG8_STAGE(PG8_SA(1, 0), a3, voffA);
;             PG8_WAIT_V(8); PG8_WAIT_L(0); PG8_BAR; PG8_MMA(1, 0, At, B0); PG8_MMA(1, 1, At, B1); PG8_BAR; PG8_SCHED;
;     ...
;         if constexpr (ALIGN_EPI) { if (wr == 0) PG8_BAR; }
	s_add_i32 s82, 0, 0x18000
	s_add_i32 s83, 0, 0x1c000
	v_add_u32_e32 v176, s82, v160
	v_add_u32_e32 v192, s83, v160
	ds_read_b128 v[164:167], v176
	ds_read_b128 v[168:171], v176 offset:1024
	ds_read_b128 v[172:175], v176 offset:2048
	ds_read_b128 v[176:179], v176 offset:3072
	ds_read_b128 v[180:183], v192
	ds_read_b128 v[184:187], v192 offset:1024
	ds_read_b128 v[188:191], v192 offset:2048
	ds_read_b128 v[192:195], v192 offset:3072
	s_add_u32 s24, s24, 0x40000
	s_addc_u32 s25, s25, 0
	s_mov_b32 m0, s37
	ds_read_b128 v[196:199], v163 offset:32768
	ds_read_b128 v[200:203], v163 offset:33792
	ds_read_b128 v[216:219], v163 offset:34816
	ds_read_b128 v[220:223], v163 offset:35840
	ds_read_b128 v[224:227], v163 offset:36864
	ds_read_b128 v[228:231], v163 offset:37888
	ds_read_b128 v[232:235], v163 offset:38912
	ds_read_b128 v[236:239], v163 offset:39936
	global_load_lds_dwordx4 v146, s[24:25]
	s_mov_b32 m0, s38
	s_nop 0
	global_load_lds_dwordx4 v150, s[24:25]
	s_waitcnt vmcnt(8) lgkmcnt(0)
	s_barrier
	s_setprio 1
	v_mfma_f32_16x16x32_bf16 v[142:145], v[164:167], v[196:199], v[142:145]
	v_mfma_f32_16x16x32_bf16 v[138:141], v[172:175], v[196:199], v[138:141]
	v_mfma_f32_16x16x32_bf16 v[126:129], v[164:167], v[216:219], v[126:129]
	v_mfma_f32_16x16x32_bf16 v[122:125], v[172:175], v[216:219], v[122:125]
	v_mfma_f32_16x16x32_bf16 v[110:113], v[164:167], v[224:227], v[110:113]
	v_mfma_f32_16x16x32_bf16 v[106:109], v[172:175], v[224:227], v[106:109]
	v_mfma_f32_16x16x32_bf16 v[94:97], v[164:167], v[232:235], v[94:97]
	v_mfma_f32_16x16x32_bf16 v[90:93], v[172:175], v[232:235], v[90:93]
	v_mfma_f32_16x16x32_bf16 v[142:145], v[168:171], v[200:203], v[142:145]
	v_mfma_f32_16x16x32_bf16 v[138:141], v[176:179], v[200:203], v[138:141]
	v_mfma_f32_16x16x32_bf16 v[126:129], v[168:171], v[220:223], v[126:129]
	v_mfma_f32_16x16x32_bf16 v[122:125], v[176:179], v[220:223], v[122:125]
	v_mfma_f32_16x16x32_bf16 v[110:113], v[168:171], v[228:231], v[110:113]
	v_mfma_f32_16x16x32_bf16 v[106:109], v[176:179], v[228:231], v[106:109]
	v_mfma_f32_16x16x32_bf16 v[94:97], v[168:171], v[236:239], v[94:97]
	v_mfma_f32_16x16x32_bf16 v[90:93], v[176:179], v[236:239], v[90:93]
	v_mfma_f32_16x16x32_bf16 v[134:137], v[180:183], v[196:199], v[134:137]
	v_mfma_f32_16x16x32_bf16 v[130:133], v[188:191], v[196:199], v[130:133]
	v_mfma_f32_16x16x32_bf16 v[118:121], v[180:183], v[216:219], v[118:121]
	v_mfma_f32_16x16x32_bf16 v[114:117], v[188:191], v[216:219], v[114:117]
	v_mfma_f32_16x16x32_bf16 v[102:105], v[180:183], v[224:227], v[102:105]
	v_mfma_f32_16x16x32_bf16 v[98:101], v[188:191], v[224:227], v[98:101]
	v_mfma_f32_16x16x32_bf16 v[86:89], v[180:183], v[232:235], v[86:89]
	v_mfma_f32_16x16x32_bf16 v[82:85], v[188:191], v[232:235], v[82:85]
	v_mfma_f32_16x16x32_bf16 v[134:137], v[184:187], v[200:203], v[134:137]
	v_mfma_f32_16x16x32_bf16 v[130:133], v[192:195], v[200:203], v[130:133]
	v_mfma_f32_16x16x32_bf16 v[118:121], v[184:187], v[220:223], v[118:121]
	v_mfma_f32_16x16x32_bf16 v[114:117], v[192:195], v[220:223], v[114:117]
	v_mfma_f32_16x16x32_bf16 v[102:105], v[184:187], v[228:231], v[102:105]
	v_mfma_f32_16x16x32_bf16 v[98:101], v[192:195], v[228:231], v[98:101]
	v_mfma_f32_16x16x32_bf16 v[86:89], v[184:187], v[236:239], v[86:89]
	v_mfma_f32_16x16x32_bf16 v[82:85], v[192:195], v[236:239], v[82:85]
	s_setprio 0
	s_barrier
	s_add_i32 s24, s82, s34
	s_mov_b32 m0, s24
	ds_read_b128 v[196:199], v163 offset:49152
	ds_read_b128 v[200:203], v163 offset:50176
	ds_read_b128 v[216:219], v163 offset:51200
	ds_read_b128 v[220:223], v163 offset:52224
	ds_read_b128 v[224:227], v163 offset:53248
	ds_read_b128 v[228:231], v163 offset:54272
	ds_read_b128 v[232:235], v163 offset:55296
	ds_read_b128 v[236:239], v163 offset:56320
	global_load_lds_dwordx4 v148, s[98:99]
	s_add_i32 m0, s24, 0x2000
	s_add_u32 s22, s22, 0x40080
	s_addc_u32 s23, s23, 0
	s_add_i32 s24, s83, s34
	global_load_lds_dwordx4 v152, s[98:99]
	s_mov_b32 m0, s24
	s_nop 0
	global_load_lds_dwordx4 v148, s[22:23]
	s_add_i32 m0, s24, 0x2000
	s_nop 0
	global_load_lds_dwordx4 v152, s[22:23]
	s_mov_b32 m0, s39
	s_nop 0
	global_load_lds_dwordx4 v146, s[100:101]
	s_mov_b32 m0, s42
	s_nop 0
	global_load_lds_dwordx4 v150, s[100:101]
	s_waitcnt vmcnt(8) lgkmcnt(0)
	s_barrier
	s_setprio 1
	v_mfma_f32_16x16x32_bf16 v[78:81], v[164:167], v[196:199], v[78:81]
	v_mfma_f32_16x16x32_bf16 v[74:77], v[172:175], v[196:199], v[74:77]
	v_mfma_f32_16x16x32_bf16 v[62:65], v[164:167], v[216:219], v[62:65]
	v_mfma_f32_16x16x32_bf16 v[58:61], v[172:175], v[216:219], v[58:61]
	v_mfma_f32_16x16x32_bf16 v[46:49], v[164:167], v[224:227], v[46:49]
	v_mfma_f32_16x16x32_bf16 v[42:45], v[172:175], v[224:227], v[42:45]
	v_mfma_f32_16x16x32_bf16 v[30:33], v[164:167], v[232:235], v[30:33]
	v_mfma_f32_16x16x32_bf16 v[26:29], v[172:175], v[232:235], v[26:29]
	v_mfma_f32_16x16x32_bf16 v[78:81], v[168:171], v[200:203], v[78:81]
	v_mfma_f32_16x16x32_bf16 v[74:77], v[176:179], v[200:203], v[74:77]
	v_mfma_f32_16x16x32_bf16 v[62:65], v[168:171], v[220:223], v[62:65]
	v_mfma_f32_16x16x32_bf16 v[58:61], v[176:179], v[220:223], v[58:61]
	v_mfma_f32_16x16x32_bf16 v[46:49], v[168:171], v[228:231], v[46:49]
	v_mfma_f32_16x16x32_bf16 v[42:45], v[176:179], v[228:231], v[42:45]
	v_mfma_f32_16x16x32_bf16 v[30:33], v[168:171], v[236:239], v[30:33]
	v_mfma_f32_16x16x32_bf16 v[26:29], v[176:179], v[236:239], v[26:29]
	v_mfma_f32_16x16x32_bf16 v[70:73], v[180:183], v[196:199], v[70:73]
	v_mfma_f32_16x16x32_bf16 v[66:69], v[188:191], v[196:199], v[66:69]
	v_mfma_f32_16x16x32_bf16 v[54:57], v[180:183], v[216:219], v[54:57]
	v_mfma_f32_16x16x32_bf16 v[50:53], v[188:191], v[216:219], v[50:53]
	v_mfma_f32_16x16x32_bf16 v[38:41], v[180:183], v[224:227], v[38:41]
	v_mfma_f32_16x16x32_bf16 v[34:37], v[188:191], v[224:227], v[34:37]
	v_mfma_f32_16x16x32_bf16 v[22:25], v[180:183], v[232:235], v[22:25]
	v_mfma_f32_16x16x32_bf16 v[18:21], v[188:191], v[232:235], v[18:21]
	v_mfma_f32_16x16x32_bf16 v[70:73], v[184:187], v[200:203], v[70:73]
	v_mfma_f32_16x16x32_bf16 v[66:69], v[192:195], v[200:203], v[66:69]
	v_mfma_f32_16x16x32_bf16 v[54:57], v[184:187], v[220:223], v[54:57]
	v_mfma_f32_16x16x32_bf16 v[50:53], v[192:195], v[220:223], v[50:53]
	v_mfma_f32_16x16x32_bf16 v[38:41], v[184:187], v[228:231], v[38:41]
	v_mfma_f32_16x16x32_bf16 v[34:37], v[192:195], v[228:231], v[34:37]
	v_mfma_f32_16x16x32_bf16 v[22:25], v[184:187], v[236:239], v[22:25]
	v_mfma_f32_16x16x32_bf16 v[18:21], v[192:195], v[236:239], v[18:21]
	s_setprio 0
	s_barrier
	s_add_i32 s64, s64, 2
	s_add_u32 s20, s20, 0x100
	s_addc_u32 s21, s21, 0
	s_add_u32 s62, s62, 0x100
	s_addc_u32 s63, s63, 0
	s_cmp_gt_u32 s64, 13
	s_cbranch_scc0 .LBB0_121

; __device__ __forceinline__ unsigned cvt_pk_bf16(float lo, float hi) { unsigned r; asm volatile("v_cvt_pk_bf16_f32 %0, %1, %2" : "=v"(r) : "v"(lo), "v"(hi)); return r; }
; __device__ __forceinline__ float silu_f(float g) { return g * __builtin_amdgcn_rcpf(1.0f + __expf(-g)); }
; #define PG8_BAR __builtin_amdgcn_s_barrier()
;     __device__ __forceinline__ void operator()(const f32x4 (&acc)[2][2][4][2], const Unit& u, int ui, int wr, int wc, int fr, int fq) const {
;         const int row0 = u.pm * BM + wr * 64 + fr, col0 = u.pn * HALF + wc * 32 + 8 * fq;
; #pragma unroll
;         for (int ai = 0; ai < 2; ++ai)
; #pragma unroll
;             for (int m = 0; m < 4; ++m) {
;                 const int row = row0 + ai * HALF + m * 16;
;                 const float s = rsb[(ui & 1) * 256 + ai * HALF + wr * 64 + m * 16 + fr];
;                 f32x4 g0 = acc[ai][0][m][0] * s, g1 = acc[ai][0][m][1] * s, u0 = acc[ai][1][m][0] * s, u1 = acc[ai][1][m][1] * s;
;                 u32x4 w;
;                 w.x = cvt_pk_bf16(silu_f(g0[0]) * u0[0], silu_f(g0[1]) * u0[1]); w.y = cvt_pk_bf16(silu_f(g0[2]) * u0[2], silu_f(g0[3]) * u0[3]);
;                 w.z = cvt_pk_bf16(silu_f(g1[0]) * u1[0], silu_f(g1[1]) * u1[1]); w.w = cvt_pk_bf16(silu_f(g1[2]) * u1[2], silu_f(g1[3]) * u1[3]);
;                 *(u32x4*)(H + (size_t)row * ldh + col0) = w;
;             }
;     }
; template <class Epi, class Sched, bool ALIGN_EPI = false, bool SP2 = false>
; __device__ __forceinline__ void gemm_phase(PG8_LAS unsigned char* lds, const Gemm g, const Sched& S, const Epi& E) {
;     ...
;         if constexpr (ALIGN_EPI) { if (wr == 0) PG8_BAR; }
.LBB0_128:
	s_lshl_b32 s2, s61, 10
	s_and_b32 s2, s2, 0x400
	v_add_u32_e32 v165, s2, v162
	ds_read_b32 v176, v165
	ds_read_b32 v178, v165 offset:64
	ds_read_b32 v180, v165 offset:128
	ds_read_b32 v182, v165 offset:192
	ds_read_b32 v184, v165 offset:512
	ds_read_b32 v186, v165 offset:576
	ds_read_b32 v188, v165 offset:640
	ds_read_b32 v190, v165 offset:704
	v_lshl_or_b32 v158, s45, 7, v161
	v_lshl_add_u32 v164, s44, 8, v1
	v_ashrrev_i32_e32 v159, 31, v158
	s_mov_b32 s98, 0x16000
	s_mov_b32 s99, 0
	s_mov_b32 s100, 0x6e000
	s_mov_b32 s101, 0
	v_mov_b32_e32 v172, 0xbfb8aa3b
	v_mov_b32_e32 v174, 1.0
	v_mov_b64_e32 v[166:167], s[8:9]
	v_mad_i64_i32 v[192:193], s[2:3], v164, s71, v[166:167]
	v_lshlrev_b64 v[166:167], 1, v[158:159]
	v_lshl_add_u64 v[192:193], v[192:193], 0, v[166:167]
	s_waitcnt lgkmcnt(0)
	v_pk_mul_f32 v[142:143], v[142:143], v[176:177] op_sel_hi:[1,0]
	v_pk_mul_f32 v[144:145], v[144:145], v[176:177] op_sel_hi:[1,0]
	v_pk_mul_f32 v[138:139], v[138:139], v[176:177] op_sel_hi:[1,0]
	v_pk_mul_f32 v[140:141], v[140:141], v[176:177] op_sel_hi:[1,0]
	v_pk_mul_f32 v[134:135], v[134:135], v[176:177] op_sel_hi:[1,0]
	v_pk_mul_f32 v[136:137], v[136:137], v[176:177] op_sel_hi:[1,0]
	v_pk_mul_f32 v[130:131], v[130:131], v[176:177] op_sel_hi:[1,0]
	v_pk_mul_f32 v[132:133], v[132:133], v[176:177] op_sel_hi:[1,0]
	v_pk_mul_f32 v[168:169], v[142:143], v[172:173] op_sel_hi:[1,0]
	v_pk_mul_f32 v[170:171], v[144:145], v[172:173] op_sel_hi:[1,0]
	v_exp_f32_e32 v168, v168
	v_exp_f32_e32 v169, v169
	v_exp_f32_e32 v170, v170
	v_exp_f32_e32 v171, v171
	v_pk_add_f32 v[168:169], v[168:169], v[174:175] op_sel_hi:[1,0]
	v_pk_add_f32 v[170:171], v[170:171], v[174:175] op_sel_hi:[1,0]
	v_rcp_f32_e32 v168, v168
	v_rcp_f32_e32 v169, v169
	v_rcp_f32_e32 v170, v170
	v_rcp_f32_e32 v171, v171
	v_pk_mul_f32 v[142:143], v[142:143], v[168:169]
	v_pk_mul_f32 v[144:145], v[144:145], v[170:171]
	v_pk_mul_f32 v[134:135], v[134:135], v[142:143]
	v_pk_mul_f32 v[136:137], v[136:137], v[144:145]
	v_cvt_pk_bf16_f32 v134, v134, v135
	v_cvt_pk_bf16_f32 v135, v136, v137
	v_pk_mul_f32 v[168:169], v[138:139], v[172:173] op_sel_hi:[1,0]
	v_pk_mul_f32 v[170:171], v[140:141], v[172:173] op_sel_hi:[1,0]
	v_exp_f32_e32 v168, v168
	v_exp_f32_e32 v169, v169
	v_exp_f32_e32 v170, v170
	v_exp_f32_e32 v171, v171
	v_pk_add_f32 v[168:169], v[168:169], v[174:175] op_sel_hi:[1,0]
	v_pk_add_f32 v[170:171], v[170:171], v[174:175] op_sel_hi:[1,0]
	v_rcp_f32_e32 v168, v168
	v_rcp_f32_e32 v169, v169
	v_rcp_f32_e32 v170, v170
	v_rcp_f32_e32 v171, v171
	v_pk_mul_f32 v[138:139], v[138:139], v[168:169]
	v_pk_mul_f32 v[140:141], v[140:141], v[170:171]
	v_pk_mul_f32 v[130:131], v[130:131], v[138:139]
	v_pk_mul_f32 v[132:133], v[132:133], v[140:141]
	v_cvt_pk_bf16_f32 v136, v130, v131
	v_cvt_pk_bf16_f32 v137, v132, v133
	global_store_dwordx4 v[192:193], v[134:137], off
	v_lshl_add_u64 v[192:193], v[192:193], 0, s[98:99]
	s_and_b64 vcc, exec, s[10:11]
	s_cbranch_vccz .Lalign_skip_a
	s_barrier
.Lalign_skip_a:
	v_pk_mul_f32 v[126:127], v[126:127], v[178:179] op_sel_hi:[1,0]
	v_pk_mul_f32 v[128:129], v[128:129], v[178:179] op_sel_hi:[1,0]
	v_pk_mul_f32 v[122:123], v[122:123], v[178:179] op_sel_hi:[1,0]
	v_pk_mul_f32 v[124:125], v[124:125], v[178:179] op_sel_hi:[1,0]
	v_pk_mul_f32 v[118:119], v[118:119], v[178:179] op_sel_hi:[1,0]
	v_pk_mul_f32 v[120:121], v[120:121], v[178:179] op_sel_hi:[1,0]
	v_pk_mul_f32 v[114:115], v[114:115], v[178:179] op_sel_hi:[1,0]
	v_pk_mul_f32 v[116:117], v[116:117], v[178:179] op_sel_hi:[1,0]
	v_pk_mul_f32 v[168:169], v[126:127], v[172:173] op_sel_hi:[1,0]
	v_pk_mul_f32 v[170:171], v[128:129], v[172:173] op_sel_hi:[1,0]
	v_exp_f32_e32 v168, v168
	v_exp_f32_e32 v169, v169
	v_exp_f32_e32 v170, v170
	v_exp_f32_e32 v171, v171
	v_pk_add_f32 v[168:169], v[168:169], v[174:175] op_sel_hi:[1,0]
	v_pk_add_f32 v[170:171], v[170:171], v[174:175] op_sel_hi:[1,0]
	v_rcp_f32_e32 v168, v168
	v_rcp_f32_e32 v169, v169
	v_rcp_f32_e32 v170, v170
	v_rcp_f32_e32 v171, v171
	v_pk_mul_f32 v[126:127], v[126:127], v[168:169]
	v_pk_mul_f32 v[128:129], v[128:129], v[170:171]
	v_pk_mul_f32 v[118:119], v[118:119], v[126:127]
	v_pk_mul_f32 v[120:121], v[120:121], v[128:129]
	v_cvt_pk_bf16_f32 v118, v118, v119
	v_cvt_pk_bf16_f32 v119, v120, v121
	v_pk_mul_f32 v[168:169], v[122:123], v[172:173] op_sel_hi:[1,0]
	v_pk_mul_f32 v[170:171], v[124:125], v[172:173] op_sel_hi:[1,0]
	v_exp_f32_e32 v168, v168
	v_exp_f32_e32 v169, v169
	v_exp_f32_e32 v170, v170
	v_exp_f32_e32 v171, v171
	v_pk_add_f32 v[168:169], v[168:169], v[174:175] op_sel_hi:[1,0]
	v_pk_add_f32 v[170:171], v[170:171], v[174:175] op_sel_hi:[1,0]
	v_rcp_f32_e32 v168, v168
	v_rcp_f32_e32 v169, v169
	v_rcp_f32_e32 v170, v170
	v_rcp_f32_e32 v171, v171
	v_pk_mul_f32 v[122:123], v[122:123], v[168:169]
	v_pk_mul_f32 v[124:125], v[124:125], v[170:171]
	v_pk_mul_f32 v[114:115], v[114:115], v[122:123]
	v_pk_mul_f32 v[116:117], v[116:117], v[124:125]
	v_cvt_pk_bf16_f32 v120, v114, v115
	v_cvt_pk_bf16_f32 v121, v116, v117
	global_store_dwordx4 v[192:193], v[118:121], off
	v_lshl_add_u64 v[192:193], v[192:193], 0, s[98:99]
	v_pk_mul_f32 v[110:111], v[110:111], v[180:181] op_sel_hi:[1,0]
	v_pk_mul_f32 v[112:113], v[112:113], v[180:181] op_sel_hi:[1,0]
	v_pk_mul_f32 v[106:107], v[106:107], v[180:181] op_sel_hi:[1,0]
	v_pk_mul_f32 v[108:109], v[108:109], v[180:181] op_sel_hi:[1,0]
	v_pk_mul_f32 v[102:103], v[102:103], v[180:181] op_sel_hi:[1,0]
	v_pk_mul_f32 v[104:105], v[104:105], v[180:181] op_sel_hi:[1,0]
	v_pk_mul_f32 v[98:99], v[98:99], v[180:181] op_sel_hi:[1,0]
	v_pk_mul_f32 v[100:101], v[100:101], v[180:181] op_sel_hi:[1,0]
	v_pk_mul_f32 v[168:169], v[110:111], v[172:173] op_sel_hi:[1,0]
; __device__ __forceinline__ unsigned cvt_pk_bf16(float lo, float hi) { unsigned r; asm volatile("v_cvt_pk_bf16_f32 %0, %1, %2" : "=v"(r) : "v"(lo), "v"(hi)); return r; }
; __device__ __forceinline__ float silu_f(float g) { return g * __builtin_amdgcn_rcpf(1.0f + __expf(-g)); }
;     __device__ __forceinline__ void operator()(const f32x4 (&acc)[2][2][4][2], const Unit& u, int ui, int wr, int wc, int fr, int fq) const {
;         const int row0 = u.pm * BM + wr * 64 + fr, col0 = u.pn * HALF + wc * 32 + 8 * fq;
; #pragma unroll
;         for (int ai = 0; ai < 2; ++ai)
; #pragma unroll
;             for (int m = 0; m < 4; ++m) {
;                 const int row = row0 + ai * HALF + m * 16;
;                 const float s = rsb[(ui & 1) * 256 + ai * HALF + wr * 64 + m * 16 + fr];
;                 f32x4 g0 = acc[ai][0][m][0] * s, g1 = acc[ai][0][m][1] * s, u0 = acc[ai][1][m][0] * s, u1 = acc[ai][1][m][1] * s;
;                 u32x4 w;
;                 w.x = cvt_pk_bf16(silu_f(g0[0]) * u0[0], silu_f(g0[1]) * u0[1]); w.y = cvt_pk_bf16(silu_f(g0[2]) * u0[2], silu_f(g0[3]) * u0[3]);
;                 w.z = cvt_pk_bf16(silu_f(g1[0]) * u1[0], silu_f(g1[1]) * u1[1]); w.w = cvt_pk_bf16(silu_f(g1[2]) * u1[2], silu_f(g1[3]) * u1[3]);
;                 *(u32x4*)(H + (size_t)row * ldh + col0) = w;
;             }
;     }
	v_pk_mul_f32 v[170:171], v[112:113], v[172:173] op_sel_hi:[1,0]
	v_exp_f32_e32 v168, v168
	v_exp_f32_e32 v169, v169
	v_exp_f32_e32 v170, v170
	v_exp_f32_e32 v171, v171
	v_pk_add_f32 v[168:169], v[168:169], v[174:175] op_sel_hi:[1,0]
	v_pk_add_f32 v[170:171], v[170:171], v[174:175] op_sel_hi:[1,0]
	v_rcp_f32_e32 v168, v168
	v_rcp_f32_e32 v169, v169
	v_rcp_f32_e32 v170, v170
	v_rcp_f32_e32 v171, v171
	v_pk_mul_f32 v[110:111], v[110:111], v[168:169]
	v_pk_mul_f32 v[112:113], v[112:113], v[170:171]
	v_pk_mul_f32 v[102:103], v[102:103], v[110:111]
	v_pk_mul_f32 v[104:105], v[104:105], v[112:113]
	v_cvt_pk_bf16_f32 v102, v102, v103
	v_cvt_pk_bf16_f32 v103, v104, v105
	v_pk_mul_f32 v[168:169], v[106:107], v[172:173] op_sel_hi:[1,0]
	v_pk_mul_f32 v[170:171], v[108:109], v[172:173] op_sel_hi:[1,0]
	v_exp_f32_e32 v168, v168
	v_exp_f32_e32 v169, v169
	v_exp_f32_e32 v170, v170
	v_exp_f32_e32 v171, v171
	v_pk_add_f32 v[168:169], v[168:169], v[174:175] op_sel_hi:[1,0]
	v_pk_add_f32 v[170:171], v[170:171], v[174:175] op_sel_hi:[1,0]
	v_rcp_f32_e32 v168, v168
	v_rcp_f32_e32 v169, v169
	v_rcp_f32_e32 v170, v170
	v_rcp_f32_e32 v171, v171
	v_pk_mul_f32 v[106:107], v[106:107], v[168:169]
	v_pk_mul_f32 v[108:109], v[108:109], v[170:171]
	v_pk_mul_f32 v[98:99], v[98:99], v[106:107]
	v_pk_mul_f32 v[100:101], v[100:101], v[108:109]
	v_cvt_pk_bf16_f32 v104, v98, v99
	v_cvt_pk_bf16_f32 v105, v100, v101
	global_store_dwordx4 v[192:193], v[102:105], off
	v_lshl_add_u64 v[192:193], v[192:193], 0, s[98:99]
	v_pk_mul_f32 v[94:95], v[94:95], v[182:183] op_sel_hi:[1,0]
	v_pk_mul_f32 v[96:97], v[96:97], v[182:183] op_sel_hi:[1,0]
	v_pk_mul_f32 v[90:91], v[90:91], v[182:183] op_sel_hi:[1,0]
	v_pk_mul_f32 v[92:93], v[92:93], v[182:183] op_sel_hi:[1,0]
	v_pk_mul_f32 v[86:87], v[86:87], v[182:183] op_sel_hi:[1,0]
	v_pk_mul_f32 v[88:89], v[88:89], v[182:183] op_sel_hi:[1,0]
	v_pk_mul_f32 v[82:83], v[82:83], v[182:183] op_sel_hi:[1,0]
	v_pk_mul_f32 v[84:85], v[84:85], v[182:183] op_sel_hi:[1,0]
	v_pk_mul_f32 v[168:169], v[94:95], v[172:173] op_sel_hi:[1,0]
	v_pk_mul_f32 v[170:171], v[96:97], v[172:173] op_sel_hi:[1,0]
	v_exp_f32_e32 v168, v168
	v_exp_f32_e32 v169, v169
	v_exp_f32_e32 v170, v170
	v_exp_f32_e32 v171, v171
	v_pk_add_f32 v[168:169], v[168:169], v[174:175] op_sel_hi:[1,0]
	v_pk_add_f32 v[170:171], v[170:171], v[174:175] op_sel_hi:[1,0]
	v_rcp_f32_e32 v168, v168
	v_rcp_f32_e32 v169, v169
	v_rcp_f32_e32 v170, v170
	v_rcp_f32_e32 v171, v171
	v_pk_mul_f32 v[94:95], v[94:95], v[168:169]
	v_pk_mul_f32 v[96:97], v[96:97], v[170:171]
	v_pk_mul_f32 v[86:87], v[86:87], v[94:95]
	v_pk_mul_f32 v[88:89], v[88:89], v[96:97]
	v_cvt_pk_bf16_f32 v86, v86, v87
	v_cvt_pk_bf16_f32 v87, v88, v89
	v_pk_mul_f32 v[168:169], v[90:91], v[172:173] op_sel_hi:[1,0]
	v_pk_mul_f32 v[170:171], v[92:93], v[172:173] op_sel_hi:[1,0]
	v_exp_f32_e32 v168, v168
	v_exp_f32_e32 v169, v169
	v_exp_f32_e32 v170, v170
	v_exp_f32_e32 v171, v171
	v_pk_add_f32 v[168:169], v[168:169], v[174:175] op_sel_hi:[1,0]
	v_pk_add_f32 v[170:171], v[170:171], v[174:175] op_sel_hi:[1,0]
	v_rcp_f32_e32 v168, v168
	v_rcp_f32_e32 v169, v169
	v_rcp_f32_e32 v170, v170
	v_rcp_f32_e32 v171, v171
	v_pk_mul_f32 v[90:91], v[90:91], v[168:169]
	v_pk_mul_f32 v[92:93], v[92:93], v[170:171]
	v_pk_mul_f32 v[82:83], v[82:83], v[90:91]
	v_pk_mul_f32 v[84:85], v[84:85], v[92:93]
	v_cvt_pk_bf16_f32 v88, v82, v83
	v_cvt_pk_bf16_f32 v89, v84, v85
	global_store_dwordx4 v[192:193], v[86:89], off
	v_lshl_add_u64 v[192:193], v[192:193], 0, s[100:101]
	v_pk_mul_f32 v[78:79], v[78:79], v[184:185] op_sel_hi:[1,0]
	v_pk_mul_f32 v[80:81], v[80:81], v[184:185] op_sel_hi:[1,0]
	v_pk_mul_f32 v[74:75], v[74:75], v[184:185] op_sel_hi:[1,0]
	v_pk_mul_f32 v[76:77], v[76:77], v[184:185] op_sel_hi:[1,0]
	v_pk_mul_f32 v[70:71], v[70:71], v[184:185] op_sel_hi:[1,0]
	v_pk_mul_f32 v[72:73], v[72:73], v[184:185] op_sel_hi:[1,0]
	v_pk_mul_f32 v[66:67], v[66:67], v[184:185] op_sel_hi:[1,0]
	v_pk_mul_f32 v[68:69], v[68:69], v[184:185] op_sel_hi:[1,0]
	v_pk_mul_f32 v[168:169], v[78:79], v[172:173] op_sel_hi:[1,0]
	v_pk_mul_f32 v[170:171], v[80:81], v[172:173] op_sel_hi:[1,0]
	v_exp_f32_e32 v168, v168
	v_exp_f32_e32 v169, v169
	v_exp_f32_e32 v170, v170
	v_exp_f32_e32 v171, v171
	v_pk_add_f32 v[168:169], v[168:169], v[174:175] op_sel_hi:[1,0]
	v_pk_add_f32 v[170:171], v[170:171], v[174:175] op_sel_hi:[1,0]
	v_rcp_f32_e32 v168, v168
	v_rcp_f32_e32 v169, v169
	v_rcp_f32_e32 v170, v170
	v_rcp_f32_e32 v171, v171
	v_pk_mul_f32 v[78:79], v[78:79], v[168:169]
	v_pk_mul_f32 v[80:81], v[80:81], v[170:171]
	v_pk_mul_f32 v[70:71], v[70:71], v[78:79]
	v_pk_mul_f32 v[72:73], v[72:73], v[80:81]
	v_cvt_pk_bf16_f32 v70, v70, v71
	v_cvt_pk_bf16_f32 v71, v72, v73
	v_pk_mul_f32 v[168:169], v[74:75], v[172:173] op_sel_hi:[1,0]
	v_pk_mul_f32 v[170:171], v[76:77], v[172:173] op_sel_hi:[1,0]
	v_exp_f32_e32 v168, v168
	v_exp_f32_e32 v169, v169
	v_exp_f32_e32 v170, v170
	v_exp_f32_e32 v171, v171
	v_pk_add_f32 v[168:169], v[168:169], v[174:175] op_sel_hi:[1,0]
	v_pk_add_f32 v[170:171], v[170:171], v[174:175] op_sel_hi:[1,0]
	v_rcp_f32_e32 v168, v168
	v_rcp_f32_e32 v169, v169
	v_rcp_f32_e32 v170, v170
	v_rcp_f32_e32 v171, v171
	v_pk_mul_f32 v[74:75], v[74:75], v[168:169]
	v_pk_mul_f32 v[76:77], v[76:77], v[170:171]
	v_pk_mul_f32 v[66:67], v[66:67], v[74:75]
	v_pk_mul_f32 v[68:69], v[68:69], v[76:77]
	v_cvt_pk_bf16_f32 v72, v66, v67
	v_cvt_pk_bf16_f32 v73, v68, v69
	global_store_dwordx4 v[192:193], v[70:73], off
	v_lshl_add_u64 v[192:193], v[192:193], 0, s[98:99]
	v_pk_mul_f32 v[62:63], v[62:63], v[186:187] op_sel_hi:[1,0]
	v_pk_mul_f32 v[64:65], v[64:65], v[186:187] op_sel_hi:[1,0]
; __device__ __forceinline__ unsigned cvt_pk_bf16(float lo, float hi) { unsigned r; asm volatile("v_cvt_pk_bf16_f32 %0, %1, %2" : "=v"(r) : "v"(lo), "v"(hi)); return r; }
; __device__ __forceinline__ float silu_f(float g) { return g * __builtin_amdgcn_rcpf(1.0f + __expf(-g)); }
;     __device__ __forceinline__ void operator()(const f32x4 (&acc)[2][2][4][2], const Unit& u, int ui, int wr, int wc, int fr, int fq) const {
;         const int row0 = u.pm * BM + wr * 64 + fr, col0 = u.pn * HALF + wc * 32 + 8 * fq;
; #pragma unroll
;         for (int ai = 0; ai < 2; ++ai)
; #pragma unroll
;             for (int m = 0; m < 4; ++m) {
;                 const int row = row0 + ai * HALF + m * 16;
;                 const float s = rsb[(ui & 1) * 256 + ai * HALF + wr * 64 + m * 16 + fr];
;                 f32x4 g0 = acc[ai][0][m][0] * s, g1 = acc[ai][0][m][1] * s, u0 = acc[ai][1][m][0] * s, u1 = acc[ai][1][m][1] * s;
;                 u32x4 w;
;                 w.x = cvt_pk_bf16(silu_f(g0[0]) * u0[0], silu_f(g0[1]) * u0[1]); w.y = cvt_pk_bf16(silu_f(g0[2]) * u0[2], silu_f(g0[3]) * u0[3]);
;                 w.z = cvt_pk_bf16(silu_f(g1[0]) * u1[0], silu_f(g1[1]) * u1[1]); w.w = cvt_pk_bf16(silu_f(g1[2]) * u1[2], silu_f(g1[3]) * u1[3]);
;                 *(u32x4*)(H + (size_t)row * ldh + col0) = w;
;             }
;     }
; template <class Epi, class Sched, bool ALIGN_EPI = false, bool SP2 = false>
; __device__ __forceinline__ void gemm_phase(PG8_LAS unsigned char* lds, const Gemm g, const Sched& S, const Epi& E) {
;     ...
;         if (!has_next) break;
	v_pk_mul_f32 v[58:59], v[58:59], v[186:187] op_sel_hi:[1,0]
	v_pk_mul_f32 v[60:61], v[60:61], v[186:187] op_sel_hi:[1,0]
	v_pk_mul_f32 v[54:55], v[54:55], v[186:187] op_sel_hi:[1,0]
	v_pk_mul_f32 v[56:57], v[56:57], v[186:187] op_sel_hi:[1,0]
	v_pk_mul_f32 v[50:51], v[50:51], v[186:187] op_sel_hi:[1,0]
	v_pk_mul_f32 v[52:53], v[52:53], v[186:187] op_sel_hi:[1,0]
	v_pk_mul_f32 v[168:169], v[62:63], v[172:173] op_sel_hi:[1,0]
	v_pk_mul_f32 v[170:171], v[64:65], v[172:173] op_sel_hi:[1,0]
	v_exp_f32_e32 v168, v168
	v_exp_f32_e32 v169, v169
	v_exp_f32_e32 v170, v170
	v_exp_f32_e32 v171, v171
	v_pk_add_f32 v[168:169], v[168:169], v[174:175] op_sel_hi:[1,0]
	v_pk_add_f32 v[170:171], v[170:171], v[174:175] op_sel_hi:[1,0]
	v_rcp_f32_e32 v168, v168
	v_rcp_f32_e32 v169, v169
	v_rcp_f32_e32 v170, v170
	v_rcp_f32_e32 v171, v171
	v_pk_mul_f32 v[62:63], v[62:63], v[168:169]
	v_pk_mul_f32 v[64:65], v[64:65], v[170:171]
	v_pk_mul_f32 v[54:55], v[54:55], v[62:63]
	v_pk_mul_f32 v[56:57], v[56:57], v[64:65]
	v_cvt_pk_bf16_f32 v54, v54, v55
	v_cvt_pk_bf16_f32 v55, v56, v57
	v_pk_mul_f32 v[168:169], v[58:59], v[172:173] op_sel_hi:[1,0]
	v_pk_mul_f32 v[170:171], v[60:61], v[172:173] op_sel_hi:[1,0]
	v_exp_f32_e32 v168, v168
	v_exp_f32_e32 v169, v169
	v_exp_f32_e32 v170, v170
	v_exp_f32_e32 v171, v171
	v_pk_add_f32 v[168:169], v[168:169], v[174:175] op_sel_hi:[1,0]
	v_pk_add_f32 v[170:171], v[170:171], v[174:175] op_sel_hi:[1,0]
	v_rcp_f32_e32 v168, v168
	v_rcp_f32_e32 v169, v169
	v_rcp_f32_e32 v170, v170
	v_rcp_f32_e32 v171, v171
	v_pk_mul_f32 v[58:59], v[58:59], v[168:169]
	v_pk_mul_f32 v[60:61], v[60:61], v[170:171]
	v_pk_mul_f32 v[50:51], v[50:51], v[58:59]
	v_pk_mul_f32 v[52:53], v[52:53], v[60:61]
	v_cvt_pk_bf16_f32 v56, v50, v51
	v_cvt_pk_bf16_f32 v57, v52, v53
	global_store_dwordx4 v[192:193], v[54:57], off
	v_lshl_add_u64 v[192:193], v[192:193], 0, s[98:99]
	v_pk_mul_f32 v[46:47], v[46:47], v[188:189] op_sel_hi:[1,0]
	v_pk_mul_f32 v[48:49], v[48:49], v[188:189] op_sel_hi:[1,0]
	v_pk_mul_f32 v[42:43], v[42:43], v[188:189] op_sel_hi:[1,0]
	v_pk_mul_f32 v[44:45], v[44:45], v[188:189] op_sel_hi:[1,0]
	v_pk_mul_f32 v[38:39], v[38:39], v[188:189] op_sel_hi:[1,0]
	v_pk_mul_f32 v[40:41], v[40:41], v[188:189] op_sel_hi:[1,0]
	v_pk_mul_f32 v[34:35], v[34:35], v[188:189] op_sel_hi:[1,0]
	v_pk_mul_f32 v[36:37], v[36:37], v[188:189] op_sel_hi:[1,0]
	v_pk_mul_f32 v[168:169], v[46:47], v[172:173] op_sel_hi:[1,0]
	v_pk_mul_f32 v[170:171], v[48:49], v[172:173] op_sel_hi:[1,0]
	v_exp_f32_e32 v168, v168
	v_exp_f32_e32 v169, v169
	v_exp_f32_e32 v170, v170
	v_exp_f32_e32 v171, v171
	v_pk_add_f32 v[168:169], v[168:169], v[174:175] op_sel_hi:[1,0]
	v_pk_add_f32 v[170:171], v[170:171], v[174:175] op_sel_hi:[1,0]
	v_rcp_f32_e32 v168, v168
	v_rcp_f32_e32 v169, v169
	v_rcp_f32_e32 v170, v170
	v_rcp_f32_e32 v171, v171
	v_pk_mul_f32 v[46:47], v[46:47], v[168:169]
	v_pk_mul_f32 v[48:49], v[48:49], v[170:171]
	v_pk_mul_f32 v[38:39], v[38:39], v[46:47]
	v_pk_mul_f32 v[40:41], v[40:41], v[48:49]
	v_cvt_pk_bf16_f32 v38, v38, v39
	v_cvt_pk_bf16_f32 v39, v40, v41
	v_pk_mul_f32 v[168:169], v[42:43], v[172:173] op_sel_hi:[1,0]
	v_pk_mul_f32 v[170:171], v[44:45], v[172:173] op_sel_hi:[1,0]
	v_exp_f32_e32 v168, v168
	v_exp_f32_e32 v169, v169
	v_exp_f32_e32 v170, v170
	v_exp_f32_e32 v171, v171
	v_pk_add_f32 v[168:169], v[168:169], v[174:175] op_sel_hi:[1,0]
	v_pk_add_f32 v[170:171], v[170:171], v[174:175] op_sel_hi:[1,0]
	v_rcp_f32_e32 v168, v168
	v_rcp_f32_e32 v169, v169
	v_rcp_f32_e32 v170, v170
	v_rcp_f32_e32 v171, v171
	v_pk_mul_f32 v[42:43], v[42:43], v[168:169]
	v_pk_mul_f32 v[44:45], v[44:45], v[170:171]
	v_pk_mul_f32 v[34:35], v[34:35], v[42:43]
	v_pk_mul_f32 v[36:37], v[36:37], v[44:45]
	v_cvt_pk_bf16_f32 v40, v34, v35
	v_cvt_pk_bf16_f32 v41, v36, v37
	global_store_dwordx4 v[192:193], v[38:41], off
	v_lshl_add_u64 v[192:193], v[192:193], 0, s[98:99]
	v_pk_mul_f32 v[30:31], v[30:31], v[190:191] op_sel_hi:[1,0]
	v_pk_mul_f32 v[32:33], v[32:33], v[190:191] op_sel_hi:[1,0]
	v_pk_mul_f32 v[26:27], v[26:27], v[190:191] op_sel_hi:[1,0]
	v_pk_mul_f32 v[28:29], v[28:29], v[190:191] op_sel_hi:[1,0]
	v_pk_mul_f32 v[22:23], v[22:23], v[190:191] op_sel_hi:[1,0]
	v_pk_mul_f32 v[24:25], v[24:25], v[190:191] op_sel_hi:[1,0]
	v_pk_mul_f32 v[18:19], v[18:19], v[190:191] op_sel_hi:[1,0]
	v_pk_mul_f32 v[20:21], v[20:21], v[190:191] op_sel_hi:[1,0]
	v_pk_mul_f32 v[168:169], v[30:31], v[172:173] op_sel_hi:[1,0]
	v_pk_mul_f32 v[170:171], v[32:33], v[172:173] op_sel_hi:[1,0]
	v_exp_f32_e32 v168, v168
	v_exp_f32_e32 v169, v169
	v_exp_f32_e32 v170, v170
	v_exp_f32_e32 v171, v171
	v_pk_add_f32 v[168:169], v[168:169], v[174:175] op_sel_hi:[1,0]
	v_pk_add_f32 v[170:171], v[170:171], v[174:175] op_sel_hi:[1,0]
	v_rcp_f32_e32 v168, v168
	v_rcp_f32_e32 v169, v169
	v_rcp_f32_e32 v170, v170
	v_rcp_f32_e32 v171, v171
	v_pk_mul_f32 v[30:31], v[30:31], v[168:169]
	v_pk_mul_f32 v[32:33], v[32:33], v[170:171]
	v_pk_mul_f32 v[22:23], v[22:23], v[30:31]
	v_pk_mul_f32 v[24:25], v[24:25], v[32:33]
	v_cvt_pk_bf16_f32 v22, v22, v23
	v_cvt_pk_bf16_f32 v23, v24, v25
	v_pk_mul_f32 v[168:169], v[26:27], v[172:173] op_sel_hi:[1,0]
	v_pk_mul_f32 v[170:171], v[28:29], v[172:173] op_sel_hi:[1,0]
	v_exp_f32_e32 v168, v168
	v_exp_f32_e32 v169, v169
	v_exp_f32_e32 v170, v170
	v_exp_f32_e32 v171, v171
	v_pk_add_f32 v[168:169], v[168:169], v[174:175] op_sel_hi:[1,0]
	v_pk_add_f32 v[170:171], v[170:171], v[174:175] op_sel_hi:[1,0]
	v_rcp_f32_e32 v168, v168
	v_rcp_f32_e32 v169, v169
	v_rcp_f32_e32 v170, v170
	v_rcp_f32_e32 v171, v171
	v_pk_mul_f32 v[26:27], v[26:27], v[168:169]
	v_pk_mul_f32 v[28:29], v[28:29], v[170:171]
	v_pk_mul_f32 v[18:19], v[18:19], v[26:27]
	v_pk_mul_f32 v[20:21], v[20:21], v[28:29]
	v_cvt_pk_bf16_f32 v24, v18, v19
	v_cvt_pk_bf16_f32 v25, v20, v21
	s_mov_b64 s[2:3], -1
	s_cmp_eq_u32 s61, 10
	global_store_dwordx4 v[192:193], v[22:25], off
	s_cbranch_scc1 .LBB0_117
;     static __device__ __forceinline__ float fin(const f32x4& a, const f32x4& b, const f32x4& c, const f32x4& d) {
;         const float s = (((a[0] + a[1]) + (a[2] + a[3])) + ((b[0] + b[1]) + (b[2] + b[3]))) + (((c[0] + c[1]) + (c[2] + c[3])) + ((d[0] + d[1]) + (d[2] + d[3])));
;         return 1.0f / sqrtf(s * (1.0f / 1024.0f) + 1e-6f); }
;     __device__ __forceinline__ void commit(const Unit& u, int ui, const Pre& p) const {
;         int t = threadIdx.x; asm volatile("" : "+v"(t));
;         if (t < 256) rsb[(ui & 1) * 256 + t] = fin(p.a, p.b, p.c, p.d);
;     }
	s_nop 0
	v_add_u32_e32 v18, 0xffffff00, v204
	s_nop 0
	v_cmp_gt_u32_e32 vcc, s68, v18
	s_and_saveexec_b64 s[20:21], vcc
	s_cbranch_execz .LBB0_131
	s_waitcnt vmcnt(8)
	v_mov_b32_e32 v20, v6
	v_mov_b32_e32 v21, v14
	v_mov_b32_e32 v22, v7
	v_mov_b32_e32 v23, v15
	v_pk_add_f32 v[20:21], v[20:21], v[22:23]
	v_mov_b32_e32 v22, v8
	v_mov_b32_e32 v23, v16
	v_mov_b32_e32 v24, v9
	v_mov_b32_e32 v25, v17
	v_pk_add_f32 v[22:23], v[22:23], v[24:25]
	v_mov_b32_e32 v24, v3
	v_pk_add_f32 v[20:21], v[20:21], v[22:23]
	v_mov_b32_e32 v22, v2
	v_mov_b32_e32 v23, v10
	v_mov_b32_e32 v25, v11
	v_pk_add_f32 v[22:23], v[22:23], v[24:25]
	v_mov_b32_e32 v24, v4
	v_mov_b32_e32 v25, v12
	v_mov_b32_e32 v26, v5
	v_mov_b32_e32 v27, v13
	v_pk_add_f32 v[24:25], v[24:25], v[26:27]
	s_nop 0
	v_pk_add_f32 v[22:23], v[22:23], v[24:25]
	s_nop 0
	v_pk_add_f32 v[20:21], v[22:23], v[20:21]
	s_nop 0
	v_add_f32_e32 v19, v20, v21
	v_fmamk_f32 v19, v19, 0x3a800000, v205
	v_mul_f32_e32 v20, 0x4f800000, v19
	v_cmp_gt_f32_e32 vcc, s69, v19
	s_nop 1
	v_cndmask_b32_e32 v19, v19, v20, vcc
	v_sqrt_f32_e32 v20, v19
	s_nop 0
	v_add_u32_e32 v21, -1, v20
	v_fma_f32 v22, -v21, v20, v19
	v_cmp_ge_f32_e64 s[2:3], 0, v22
	v_add_u32_e32 v22, 1, v20
	s_nop 0
	v_cndmask_b32_e64 v21, v20, v21, s[2:3]
	v_fma_f32 v20, -v22, v20, v19
	v_cmp_lt_f32_e64 s[2:3], 0, v20
	s_nop 1
	v_cndmask_b32_e64 v20, v21, v22, s[2:3]
	v_mul_f32_e32 v21, 0x37800000, v20
	v_cndmask_b32_e32 v20, v20, v21, vcc
	v_cmp_class_f32_e32 vcc, v19, v206
	s_nop 1
	v_cndmask_b32_e32 v19, v20, v19, vcc
	v_div_scale_f32 v20, s[2:3], v19, v19, 1.0
	v_rcp_f32_e32 v21, v20
	s_lshl_b32 s2, s60, 10
	s_and_b32 s2, s2, 0x400
	s_add_i32 s2, s2, 0
	v_fma_f32 v22, -v20, v21, 1.0
	v_fmac_f32_e32 v21, v22, v21
	v_div_scale_f32 v22, vcc, 1.0, v19, 1.0
	v_mul_f32_e32 v23, v22, v21
	v_fma_f32 v24, -v20, v23, v22
	v_fmac_f32_e32 v23, v24, v21
	v_fma_f32 v20, -v20, v23, v22
	v_div_fmas_f32 v20, v20, v21, v23
	v_lshl_add_u32 v18, v18, 2, s2
	v_div_fixup_f32 v19, v20, v19, 1.0
	v_add_u32_e32 v18, 0x20400, v18
	ds_write_b32 v18, v19

; #define PG8_STAGE(bufoff, gbase, voff) do { _Pragma("unroll") for (int _i = 0; _i < 2; ++_i) \
;         __builtin_amdgcn_global_load_lds((const unsigned*)((const char*)(gbase) + (voff)[_i]), (PG8_LAS unsigned*)(lds + (bufoff) + ldsw + _i * 8192), 16, 0, 0); } while (0)
; #define PG8_LDA(dst, b, h) do { _Pragma("unroll") for (int m = 0; m < 4; ++m) _Pragma("unroll") for (int k = 0; k < 2; ++k) dst[m][k] = *(const PG8_LAS bf16x8*)(lds + PG8_SA(b, h) + aoff + m * 2048 + k * 1024); } while (0)
; #define PG8_LDB(dst, b, h) do { _Pragma("unroll") for (int n = 0; n < 2; ++n) _Pragma("unroll") for (int k = 0; k < 2; ++k) dst[n][k] = *(const PG8_LAS bf16x8*)(lds + PG8_SB(b, h) + boff + n * 2048 + k * 1024); } while (0)
; #define PG8_MMA(ai, bj, At, Bt) do { __builtin_amdgcn_s_setprio(1); _Pragma("unroll") for (int m = 0; m < 4; ++m) _Pragma("unroll") for (int n = 0; n < 2; ++n) _Pragma("unroll") for (int k = 0; k < 2; ++k) \
;         acc[ai][bj][m][n] = __builtin_amdgcn_mfma_f32_16x16x32_bf16(Bt[n][k], At[m][k], acc[ai][bj][m][n], 0, 0, 0); __builtin_amdgcn_s_setprio(0); } while (0)
; #define PG8_WAIT_V(n) asm volatile("s_waitcnt vmcnt(" #n ")" ::: "memory")
; #define PG8_WAIT_L(n) asm volatile("s_waitcnt lgkmcnt(" #n ")" ::: "memory")
; #define PG8_BAR __builtin_amdgcn_s_barrier()
; #define PG8_SCHED __builtin_amdgcn_sched_barrier(0)
; template <class Epi, class Sched, bool ALIGN_EPI = false, bool SP2 = false>
; __device__ __forceinline__ void gemm_phase(PG8_LAS unsigned char* lds, const Gemm g, const Sched& S, const Epi& E) {
;     ...
;             PG8_LDB(B0, 0, 0); PG8_LDB(B1, 0, 1); PG8_SCHED; PG8_LDA(At, 0, 0); PG8_STAGE(PG8_SA(1, 1), a1 + hstep, voffA);
;             PG8_WAIT_V(8); PG8_WAIT_L(0); PG8_BAR; PG8_MMA(0, 0, At, B0); PG8_MMA(0, 1, At, B1); PG8_BAR; PG8_SCHED;
;             PG8_LDA(At, 0, 1); PG8_STAGE(PG8_SB(0, 0), b2, voffB); PG8_STAGE(PG8_SB(0, 1), b2 + hstep, voffB); PG8_STAGE(PG8_SA(0, 0), a2, voffA);
;             PG8_WAIT_V(8); PG8_WAIT_L(0); PG8_BAR; PG8_MMA(1, 0, At, B0); PG8_MMA(1, 1, At, B1); PG8_BAR; PG8_SCHED;
.LBB0_762:
	v_add_u32_e32 v158, s90, v160
	ds_read_b128 v[164:167], v158
	ds_read_b128 v[168:171], v158 offset:1024
	ds_read_b128 v[172:175], v158 offset:2048
	ds_read_b128 v[176:179], v158 offset:3072
	v_add_u32_e32 v158, s81, v160
	ds_read_b128 v[180:183], v158
	ds_read_b128 v[184:187], v158 offset:1024
	ds_read_b128 v[188:191], v158 offset:2048
	ds_read_b128 v[192:195], v158 offset:3072
	s_add_u32 s22, s20, 0xfffc0080
	s_addc_u32 s23, s21, -1
	s_cmp_eq_u32 s64, 12
	s_cselect_b32 s25, s13, s23
	s_cselect_b32 s24, s52, s22
	s_cselect_b32 s23, s15, s63
	s_cselect_b32 s22, s53, s62
	s_add_u32 s98, s22, s46
	s_addc_u32 s99, s23, s47
	s_add_u32 s100, s24, s46
	s_addc_u32 s101, s25, s47
	s_add_i32 m0, s35, 0xc000
	ds_read_b128 v[196:199], v163
	ds_read_b128 v[200:203], v163 offset:1024
	ds_read_b128 v[216:219], v163 offset:2048
	ds_read_b128 v[220:223], v163 offset:3072
	ds_read_b128 v[224:227], v163 offset:4096
	ds_read_b128 v[228:231], v163 offset:5120
	ds_read_b128 v[232:235], v163 offset:6144
	ds_read_b128 v[236:239], v163 offset:7168
	global_load_lds_dwordx4 v154, s[20:21]
	s_add_i32 m0, s35, 0xe000
	s_nop 0
	global_load_lds_dwordx4 v156, s[20:21]
	s_waitcnt vmcnt(8) lgkmcnt(0)
	s_barrier
	s_setprio 1
	v_mfma_f32_16x16x32_bf16 v[142:145], v[164:167], v[196:199], v[142:145]
	v_mfma_f32_16x16x32_bf16 v[138:141], v[172:175], v[196:199], v[138:141]
	v_mfma_f32_16x16x32_bf16 v[126:129], v[164:167], v[216:219], v[126:129]
	v_mfma_f32_16x16x32_bf16 v[122:125], v[172:175], v[216:219], v[122:125]
	v_mfma_f32_16x16x32_bf16 v[110:113], v[164:167], v[224:227], v[110:113]
	v_mfma_f32_16x16x32_bf16 v[106:109], v[172:175], v[224:227], v[106:109]
	v_mfma_f32_16x16x32_bf16 v[94:97], v[164:167], v[232:235], v[94:97]
	v_mfma_f32_16x16x32_bf16 v[90:93], v[172:175], v[232:235], v[90:93]
	v_mfma_f32_16x16x32_bf16 v[142:145], v[168:171], v[200:203], v[142:145]
	v_mfma_f32_16x16x32_bf16 v[138:141], v[176:179], v[200:203], v[138:141]
	v_mfma_f32_16x16x32_bf16 v[126:129], v[168:171], v[220:223], v[126:129]
	v_mfma_f32_16x16x32_bf16 v[122:125], v[176:179], v[220:223], v[122:125]
	v_mfma_f32_16x16x32_bf16 v[110:113], v[168:171], v[228:231], v[110:113]
	v_mfma_f32_16x16x32_bf16 v[106:109], v[176:179], v[228:231], v[106:109]
	v_mfma_f32_16x16x32_bf16 v[94:97], v[168:171], v[236:239], v[94:97]
	v_mfma_f32_16x16x32_bf16 v[90:93], v[176:179], v[236:239], v[90:93]
	v_mfma_f32_16x16x32_bf16 v[134:137], v[180:183], v[196:199], v[134:137]
	v_mfma_f32_16x16x32_bf16 v[130:133], v[188:191], v[196:199], v[130:133]
	v_mfma_f32_16x16x32_bf16 v[118:121], v[180:183], v[216:219], v[118:121]
	v_mfma_f32_16x16x32_bf16 v[114:117], v[188:191], v[216:219], v[114:117]
	v_mfma_f32_16x16x32_bf16 v[102:105], v[180:183], v[224:227], v[102:105]
	v_mfma_f32_16x16x32_bf16 v[98:101], v[188:191], v[224:227], v[98:101]
	v_mfma_f32_16x16x32_bf16 v[86:89], v[180:183], v[232:235], v[86:89]
	v_mfma_f32_16x16x32_bf16 v[82:85], v[188:191], v[232:235], v[82:85]
	v_mfma_f32_16x16x32_bf16 v[134:137], v[184:187], v[200:203], v[134:137]
	v_mfma_f32_16x16x32_bf16 v[130:133], v[192:195], v[200:203], v[130:133]
	v_mfma_f32_16x16x32_bf16 v[118:121], v[184:187], v[220:223], v[118:121]
	v_mfma_f32_16x16x32_bf16 v[114:117], v[192:195], v[220:223], v[114:117]
	v_mfma_f32_16x16x32_bf16 v[102:105], v[184:187], v[228:231], v[102:105]
	v_mfma_f32_16x16x32_bf16 v[98:101], v[192:195], v[228:231], v[98:101]
	v_mfma_f32_16x16x32_bf16 v[86:89], v[184:187], v[236:239], v[86:89]
	v_mfma_f32_16x16x32_bf16 v[82:85], v[192:195], v[236:239], v[82:85]
	s_setprio 0
	s_barrier
	s_add_i32 s65, s90, s34
	s_mov_b32 m0, s65
	ds_read_b128 v[196:199], v163 offset:16384
	ds_read_b128 v[200:203], v163 offset:17408
	ds_read_b128 v[216:219], v163 offset:18432
	ds_read_b128 v[220:223], v163 offset:19456
	ds_read_b128 v[224:227], v163 offset:20480
	ds_read_b128 v[228:231], v163 offset:21504
	ds_read_b128 v[232:235], v163 offset:22528
	ds_read_b128 v[236:239], v163 offset:23552
	global_load_lds_dwordx4 v148, s[22:23]
	s_add_i32 m0, s65, 0x2000
	s_add_u32 s66, s22, 0x40000
	s_addc_u32 s67, s23, 0
	s_add_i32 s65, s81, s34
	global_load_lds_dwordx4 v152, s[22:23]
	s_mov_b32 m0, s65
	s_nop 0
	global_load_lds_dwordx4 v148, s[66:67]
	s_add_i32 m0, s65, 0x2000
	s_nop 0
	global_load_lds_dwordx4 v152, s[66:67]
	s_mov_b32 m0, s35
	s_nop 0
	global_load_lds_dwordx4 v146, s[24:25]
	s_mov_b32 m0, s36
	s_nop 0
	global_load_lds_dwordx4 v150, s[24:25]
	s_waitcnt vmcnt(8) lgkmcnt(0)
	s_barrier
	s_setprio 1
	v_mfma_f32_16x16x32_bf16 v[78:81], v[164:167], v[196:199], v[78:81]
	v_mfma_f32_16x16x32_bf16 v[74:77], v[172:175], v[196:199], v[74:77]
	v_mfma_f32_16x16x32_bf16 v[62:65], v[164:167], v[216:219], v[62:65]
	v_mfma_f32_16x16x32_bf16 v[58:61], v[172:175], v[216:219], v[58:61]
	v_mfma_f32_16x16x32_bf16 v[46:49], v[164:167], v[224:227], v[46:49]
	v_mfma_f32_16x16x32_bf16 v[42:45], v[172:175], v[224:227], v[42:45]
	v_mfma_f32_16x16x32_bf16 v[30:33], v[164:167], v[232:235], v[30:33]
	v_mfma_f32_16x16x32_bf16 v[26:29], v[172:175], v[232:235], v[26:29]
	v_mfma_f32_16x16x32_bf16 v[78:81], v[168:171], v[200:203], v[78:81]
	v_mfma_f32_16x16x32_bf16 v[74:77], v[176:179], v[200:203], v[74:77]
	v_mfma_f32_16x16x32_bf16 v[62:65], v[168:171], v[220:223], v[62:65]
	v_mfma_f32_16x16x32_bf16 v[58:61], v[176:179], v[220:223], v[58:61]
	v_mfma_f32_16x16x32_bf16 v[46:49], v[168:171], v[228:231], v[46:49]
	v_mfma_f32_16x16x32_bf16 v[42:45], v[176:179], v[228:231], v[42:45]
	v_mfma_f32_16x16x32_bf16 v[30:33], v[168:171], v[236:239], v[30:33]
	v_mfma_f32_16x16x32_bf16 v[26:29], v[176:179], v[236:239], v[26:29]
	v_mfma_f32_16x16x32_bf16 v[70:73], v[180:183], v[196:199], v[70:73]
	v_mfma_f32_16x16x32_bf16 v[66:69], v[188:191], v[196:199], v[66:69]
	v_mfma_f32_16x16x32_bf16 v[54:57], v[180:183], v[216:219], v[54:57]
	v_mfma_f32_16x16x32_bf16 v[50:53], v[188:191], v[216:219], v[50:53]
	v_mfma_f32_16x16x32_bf16 v[38:41], v[180:183], v[224:227], v[38:41]
	v_mfma_f32_16x16x32_bf16 v[34:37], v[188:191], v[224:227], v[34:37]
	v_mfma_f32_16x16x32_bf16 v[22:25], v[180:183], v[232:235], v[22:25]
	v_mfma_f32_16x16x32_bf16 v[18:21], v[188:191], v[232:235], v[18:21]
	v_mfma_f32_16x16x32_bf16 v[70:73], v[184:187], v[200:203], v[70:73]
	v_mfma_f32_16x16x32_bf16 v[66:69], v[192:195], v[200:203], v[66:69]
	v_mfma_f32_16x16x32_bf16 v[54:57], v[184:187], v[220:223], v[54:57]
	v_mfma_f32_16x16x32_bf16 v[50:53], v[192:195], v[220:223], v[50:53]
	v_mfma_f32_16x16x32_bf16 v[38:41], v[184:187], v[228:231], v[38:41]
	v_mfma_f32_16x16x32_bf16 v[34:37], v[192:195], v[228:231], v[34:37]
	v_mfma_f32_16x16x32_bf16 v[22:25], v[184:187], v[236:239], v[22:25]
	v_mfma_f32_16x16x32_bf16 v[18:21], v[192:195], v[236:239], v[18:21]
	s_setprio 0
	s_barrier
; #define PG8_STAGE(bufoff, gbase, voff) do { _Pragma("unroll") for (int _i = 0; _i < 2; ++_i) \
;         __builtin_amdgcn_global_load_lds((const unsigned*)((const char*)(gbase) + (voff)[_i]), (PG8_LAS unsigned*)(lds + (bufoff) + ldsw + _i * 8192), 16, 0, 0); } while (0)
; #define PG8_LDA(dst, b, h) do { _Pragma("unroll") for (int m = 0; m < 4; ++m) _Pragma("unroll") for (int k = 0; k < 2; ++k) dst[m][k] = *(const PG8_LAS bf16x8*)(lds + PG8_SA(b, h) + aoff + m * 2048 + k * 1024); } while (0)
; #define PG8_LDB(dst, b, h) do { _Pragma("unroll") for (int n = 0; n < 2; ++n) _Pragma("unroll") for (int k = 0; k < 2; ++k) dst[n][k] = *(const PG8_LAS bf16x8*)(lds + PG8_SB(b, h) + boff + n * 2048 + k * 1024); } while (0)
; #define PG8_MMA(ai, bj, At, Bt) do { __builtin_amdgcn_s_setprio(1); _Pragma("unroll") for (int m = 0; m < 4; ++m) _Pragma("unroll") for (int n = 0; n < 2; ++n) _Pragma("unroll") for (int k = 0; k < 2; ++k) \
;         acc[ai][bj][m][n] = __builtin_amdgcn_mfma_f32_16x16x32_bf16(Bt[n][k], At[m][k], acc[ai][bj][m][n], 0, 0, 0); __builtin_amdgcn_s_setprio(0); } while (0)
; #define PG8_WAIT_V(n) asm volatile("s_waitcnt vmcnt(" #n ")" ::: "memory")
; #define PG8_WAIT_L(n) asm volatile("s_waitcnt lgkmcnt(" #n ")" ::: "memory")
; #define PG8_BAR __builtin_amdgcn_s_barrier()
; #define PG8_SCHED __builtin_amdgcn_sched_barrier(0)
; template <class Epi, class Sched, bool ALIGN_EPI = false, bool SP2 = false>
; __device__ __forceinline__ void gemm_phase(PG8_LAS unsigned char* lds, const Gemm g, const Sched& S, const Epi& E) {
;     ...
;             PG8_LDB(B0, 1, 0); PG8_LDB(B1, 1, 1); PG8_SCHED; PG8_LDA(At, 1, 0); PG8_STAGE(PG8_SA(0, 1), a2 + hstep, voffA);
;             PG8_WAIT_V(8); PG8_WAIT_L(0); PG8_BAR; PG8_MMA(0, 0, At, B0); PG8_MMA(0, 1, At, B1); PG8_BAR; PG8_SCHED;
;             PG8_LDA(At, 1, 1); PG8_STAGE(PG8_SB(1, 0), b3, voffB); PG8_STAGE(PG8_SB(1, 1), b3 + hstep, voffB); PG8_STAGE(PG8_SA(1, 0), a3, voffA);
;             PG8_WAIT_V(8); PG8_WAIT_L(0); PG8_BAR; PG8_MMA(1, 0, At, B0); PG8_MMA(1, 1, At, B1); PG8_BAR; PG8_SCHED;
;     ...
;         if constexpr (ALIGN_EPI) { if (wr == 0) PG8_BAR; }
	v_add_u32_e32 v176, s82, v160
	v_add_u32_e32 v192, s83, v160
	ds_read_b128 v[164:167], v176
	ds_read_b128 v[168:171], v176 offset:1024
	ds_read_b128 v[172:175], v176 offset:2048
	ds_read_b128 v[176:179], v176 offset:3072
	ds_read_b128 v[180:183], v192
	ds_read_b128 v[184:187], v192 offset:1024
	ds_read_b128 v[188:191], v192 offset:2048
	ds_read_b128 v[192:195], v192 offset:3072
	s_add_u32 s24, s24, 0x40000
	s_addc_u32 s25, s25, 0
	s_mov_b32 m0, s37
	ds_read_b128 v[196:199], v163 offset:32768
	ds_read_b128 v[200:203], v163 offset:33792
	ds_read_b128 v[216:219], v163 offset:34816
	ds_read_b128 v[220:223], v163 offset:35840
	ds_read_b128 v[224:227], v163 offset:36864
	ds_read_b128 v[228:231], v163 offset:37888
	ds_read_b128 v[232:235], v163 offset:38912
	ds_read_b128 v[236:239], v163 offset:39936
	global_load_lds_dwordx4 v146, s[24:25]
	s_mov_b32 m0, s38
	s_nop 0
	global_load_lds_dwordx4 v150, s[24:25]
	s_waitcnt vmcnt(8) lgkmcnt(0)
	s_barrier
	s_setprio 1
	v_mfma_f32_16x16x32_bf16 v[142:145], v[164:167], v[196:199], v[142:145]
	v_mfma_f32_16x16x32_bf16 v[138:141], v[172:175], v[196:199], v[138:141]
	v_mfma_f32_16x16x32_bf16 v[126:129], v[164:167], v[216:219], v[126:129]
	v_mfma_f32_16x16x32_bf16 v[122:125], v[172:175], v[216:219], v[122:125]
	v_mfma_f32_16x16x32_bf16 v[110:113], v[164:167], v[224:227], v[110:113]
	v_mfma_f32_16x16x32_bf16 v[106:109], v[172:175], v[224:227], v[106:109]
	v_mfma_f32_16x16x32_bf16 v[94:97], v[164:167], v[232:235], v[94:97]
	v_mfma_f32_16x16x32_bf16 v[90:93], v[172:175], v[232:235], v[90:93]
	v_mfma_f32_16x16x32_bf16 v[142:145], v[168:171], v[200:203], v[142:145]
	v_mfma_f32_16x16x32_bf16 v[138:141], v[176:179], v[200:203], v[138:141]
	v_mfma_f32_16x16x32_bf16 v[126:129], v[168:171], v[220:223], v[126:129]
	v_mfma_f32_16x16x32_bf16 v[122:125], v[176:179], v[220:223], v[122:125]
	v_mfma_f32_16x16x32_bf16 v[110:113], v[168:171], v[228:231], v[110:113]
	v_mfma_f32_16x16x32_bf16 v[106:109], v[176:179], v[228:231], v[106:109]
	v_mfma_f32_16x16x32_bf16 v[94:97], v[168:171], v[236:239], v[94:97]
	v_mfma_f32_16x16x32_bf16 v[90:93], v[176:179], v[236:239], v[90:93]
	v_mfma_f32_16x16x32_bf16 v[134:137], v[180:183], v[196:199], v[134:137]
	v_mfma_f32_16x16x32_bf16 v[130:133], v[188:191], v[196:199], v[130:133]
	v_mfma_f32_16x16x32_bf16 v[118:121], v[180:183], v[216:219], v[118:121]
	v_mfma_f32_16x16x32_bf16 v[114:117], v[188:191], v[216:219], v[114:117]
	v_mfma_f32_16x16x32_bf16 v[102:105], v[180:183], v[224:227], v[102:105]
	v_mfma_f32_16x16x32_bf16 v[98:101], v[188:191], v[224:227], v[98:101]
	v_mfma_f32_16x16x32_bf16 v[86:89], v[180:183], v[232:235], v[86:89]
	v_mfma_f32_16x16x32_bf16 v[82:85], v[188:191], v[232:235], v[82:85]
	v_mfma_f32_16x16x32_bf16 v[134:137], v[184:187], v[200:203], v[134:137]
	v_mfma_f32_16x16x32_bf16 v[130:133], v[192:195], v[200:203], v[130:133]
	v_mfma_f32_16x16x32_bf16 v[118:121], v[184:187], v[220:223], v[118:121]
	v_mfma_f32_16x16x32_bf16 v[114:117], v[192:195], v[220:223], v[114:117]
	v_mfma_f32_16x16x32_bf16 v[102:105], v[184:187], v[228:231], v[102:105]
	v_mfma_f32_16x16x32_bf16 v[98:101], v[192:195], v[228:231], v[98:101]
	v_mfma_f32_16x16x32_bf16 v[86:89], v[184:187], v[236:239], v[86:89]
	v_mfma_f32_16x16x32_bf16 v[82:85], v[192:195], v[236:239], v[82:85]
	s_setprio 0
	s_barrier
	s_add_i32 s24, s82, s34
	s_mov_b32 m0, s24
	ds_read_b128 v[196:199], v163 offset:49152
	ds_read_b128 v[200:203], v163 offset:50176
	ds_read_b128 v[216:219], v163 offset:51200
	ds_read_b128 v[220:223], v163 offset:52224
	ds_read_b128 v[224:227], v163 offset:53248
	ds_read_b128 v[228:231], v163 offset:54272
	ds_read_b128 v[232:235], v163 offset:55296
	ds_read_b128 v[236:239], v163 offset:56320
	global_load_lds_dwordx4 v148, s[98:99]
	s_add_i32 m0, s24, 0x2000
	s_add_u32 s22, s22, 0x40080
	s_addc_u32 s23, s23, 0
	s_add_i32 s24, s83, s34
	global_load_lds_dwordx4 v152, s[98:99]
	s_mov_b32 m0, s24
	s_nop 0
	global_load_lds_dwordx4 v148, s[22:23]
	s_add_i32 m0, s24, 0x2000
	s_nop 0
	global_load_lds_dwordx4 v152, s[22:23]
	s_mov_b32 m0, s39
	s_nop 0
	global_load_lds_dwordx4 v146, s[100:101]
	s_mov_b32 m0, s42
	s_nop 0
	global_load_lds_dwordx4 v150, s[100:101]
	s_waitcnt vmcnt(8) lgkmcnt(0)
	s_barrier
	s_setprio 1
	v_mfma_f32_16x16x32_bf16 v[78:81], v[164:167], v[196:199], v[78:81]
	v_mfma_f32_16x16x32_bf16 v[74:77], v[172:175], v[196:199], v[74:77]
	v_mfma_f32_16x16x32_bf16 v[62:65], v[164:167], v[216:219], v[62:65]
	v_mfma_f32_16x16x32_bf16 v[58:61], v[172:175], v[216:219], v[58:61]
	v_mfma_f32_16x16x32_bf16 v[46:49], v[164:167], v[224:227], v[46:49]
	v_mfma_f32_16x16x32_bf16 v[42:45], v[172:175], v[224:227], v[42:45]
	v_mfma_f32_16x16x32_bf16 v[30:33], v[164:167], v[232:235], v[30:33]
	v_mfma_f32_16x16x32_bf16 v[26:29], v[172:175], v[232:235], v[26:29]
	v_mfma_f32_16x16x32_bf16 v[78:81], v[168:171], v[200:203], v[78:81]
	v_mfma_f32_16x16x32_bf16 v[74:77], v[176:179], v[200:203], v[74:77]
	v_mfma_f32_16x16x32_bf16 v[62:65], v[168:171], v[220:223], v[62:65]
	v_mfma_f32_16x16x32_bf16 v[58:61], v[176:179], v[220:223], v[58:61]
	v_mfma_f32_16x16x32_bf16 v[46:49], v[168:171], v[228:231], v[46:49]
	v_mfma_f32_16x16x32_bf16 v[42:45], v[176:179], v[228:231], v[42:45]
	v_mfma_f32_16x16x32_bf16 v[30:33], v[168:171], v[236:239], v[30:33]
	v_mfma_f32_16x16x32_bf16 v[26:29], v[176:179], v[236:239], v[26:29]
	v_mfma_f32_16x16x32_bf16 v[70:73], v[180:183], v[196:199], v[70:73]
	v_mfma_f32_16x16x32_bf16 v[66:69], v[188:191], v[196:199], v[66:69]
	v_mfma_f32_16x16x32_bf16 v[54:57], v[180:183], v[216:219], v[54:57]
	v_mfma_f32_16x16x32_bf16 v[50:53], v[188:191], v[216:219], v[50:53]
	v_mfma_f32_16x16x32_bf16 v[38:41], v[180:183], v[224:227], v[38:41]
	v_mfma_f32_16x16x32_bf16 v[34:37], v[188:191], v[224:227], v[34:37]
	v_mfma_f32_16x16x32_bf16 v[22:25], v[180:183], v[232:235], v[22:25]
	v_mfma_f32_16x16x32_bf16 v[18:21], v[188:191], v[232:235], v[18:21]
	v_mfma_f32_16x16x32_bf16 v[70:73], v[184:187], v[200:203], v[70:73]
	v_mfma_f32_16x16x32_bf16 v[66:69], v[192:195], v[200:203], v[66:69]
	v_mfma_f32_16x16x32_bf16 v[54:57], v[184:187], v[220:223], v[54:57]
	v_mfma_f32_16x16x32_bf16 v[50:53], v[192:195], v[220:223], v[50:53]
	v_mfma_f32_16x16x32_bf16 v[38:41], v[184:187], v[228:231], v[38:41]
	v_mfma_f32_16x16x32_bf16 v[34:37], v[192:195], v[228:231], v[34:37]
	v_mfma_f32_16x16x32_bf16 v[22:25], v[184:187], v[236:239], v[22:25]
	v_mfma_f32_16x16x32_bf16 v[18:21], v[192:195], v[236:239], v[18:21]
	s_setprio 0
	s_barrier
	s_add_i32 s64, s64, 2
	s_add_u32 s20, s20, 0x100
	s_addc_u32 s21, s21, 0
	s_add_u32 s62, s62, 0x100
	s_addc_u32 s63, s63, 0
	s_cmp_gt_u32 s64, 13
	s_cbranch_scc0 .LBB0_762
